# v23 + branch-A bias-class compare chain started before the mid-step barrier (asm guide 7.12 step 2): only saveexec+branch between last QK MFMA and first PV MFMA
# speedup vs baseline: 1.0008x; 1.0008x over previous
; __device__ __forceinline__ s16x4 vtr(lds_cptr p) { return __builtin_bit_cast(s16x4, __builtin_amdgcn_ds_read_tr16_b64_v4i16((__attribute__((address_space(3))) v4i16_t*)p)); }
; #define PIN(x) asm volatile("" : "+v"(x))
; template <int DK, bool NOMAX> ...
;     ...
;     if (d0 == 0) { c0 = __builtin_amdgcn_mfma_f32_32x32x16_bf16(kf[0][0], qr[0], f32x16{}, 0, 0, 0); c1 = __builtin_amdgcn_mfma_f32_32x32x16_bf16(kf[0][1], qr[0], f32x16{}, 0, 0, 0); }
;     else { c0 = __builtin_amdgcn_mfma_f32_32x32x16_bf16(kf[d0 & 1][0], qr[d0], c0, 0, 0, 0); c1 = __builtin_amdgcn_mfma_f32_32x32x16_bf16(kf[d0 & 1][1], qr[d0], c1, 0, 0, 0); }
;     if (d0 + 2 < NS) KRD_(d0 & 1, d0 + 2);
;     if constexpr (NOMAX) { }
;     else {
; #pragma unroll
;     for (int r = d0 * RPS; r < (d0 + 1) * RPS; ++r) { p1[r] = __builtin_amdgcn_exp2f(p1[r]); psa += p0[r]; }
;     if (d0 > 0) {
; #pragma unroll
;       for (int r = (d0 - 1) * RPS; r < d0 * RPS; ++r) psb += p1[r]; } }
;     if constexpr (NOMAX) {
;       if (d0 == NS / 4 - 1) { PK4R(p0, 0, pa[0]); PIN(pa[0]); }
;       if (d0 == NS / 2 - 1) { PK4R(p0, 8, pa[1]); PIN(pa[1]); }
;       if (d0 == 3 * NS / 4 - 1) { PK4R(p1, 0, pa[2]); PIN(pa[2]); }
;       if (d0 == NS - 1) { PK4R(p1, 8, pa[3]); PIN(pa[3]); }
;     } else {
;     if (d0 == NS / 2 - 1) { PK4R(p0, 0, pa[0]); PIN(pa[0]); }
;     if (d0 == NS / 2) { PK4R(p0, 8, pa[1]); PIN(pa[1]); }
;     if (d0 == NS - 1) { PK4R(p1, 0, pa[2]); PIN(pa[2]); }
;     }
;     if (d0 == NS - 1) {
;       vl[0] = vtr(vp + v_rd_off(0, 0, 0)); vh[0] = vtr(vp + v_rd_off(0, 0, 1)); vl[1] = vtr(vp + v_rd_off(1, 0, 0)); vh[1] = vtr(vp + v_rd_off(1, 0, 1)); }
;     PIN(p1); PIN(psa); PIN(psb);
.LBB0_220:
	s_mov_b32 s6, s96
	s_mov_b32 s96, s4
	s_add_i32 s4, s63, 0xffff4000
	s_and_b32 s59, s4, 0xc000
	s_add_i32 s4, s59, 0
	v_add_u32_e32 v213, s96, v187
	s_waitcnt lgkmcnt(0)
	v_mfma_f32_32x32x16_bf16 v[128:143], v[116:119], v[156:159], 0
	v_add_u32_e32 v0, s4, v207
	ds_read_b128 v[2:5], v0
	ds_read_b128 v[164:167], v0 offset:4096
	v_cvt_pk_bf16_f32 v96, v96, v97
	v_cvt_pk_bf16_f32 v97, v98, v99
	v_cvt_pk_bf16_f32 v98, v100, v101
	v_cvt_pk_bf16_f32 v99, v102, v103
	v_mfma_f32_32x32x16_bf16 v[112:127], v[112:115], v[156:159], 0
	v_permlane32_swap_b32_e32 v96, v98
	v_permlane32_swap_b32_e32 v97, v99
	v_mfma_f32_32x32x16_bf16 v[128:143], v[10:13], v[152:155], v[128:143]
	v_mfma_f32_32x32x16_bf16 v[112:127], v[6:9], v[152:155], v[112:127]
	v_add_u32_e32 v6, s4, v208
	ds_read_b128 v[100:103], v6
	ds_read_b128 v[214:217], v6 offset:4096
	v_cvt_pk_bf16_f32 v10, v104, v105
	v_cvt_pk_bf16_f32 v11, v106, v107
	v_cvt_pk_bf16_f32 v12, v108, v109
	v_cvt_pk_bf16_f32 v13, v110, v111
	s_nop 0
	v_permlane32_swap_b32_e32 v10, v12
	v_permlane32_swap_b32_e32 v11, v13
	s_waitcnt lgkmcnt(3)
	v_mfma_f32_32x32x16_bf16 v[128:143], v[2:5], v[148:151], v[128:143]
	v_cvt_pk_bf16_f32 v6, v80, v81
	v_cvt_pk_bf16_f32 v7, v82, v83
	v_cvt_pk_bf16_f32 v8, v84, v85
	v_cvt_pk_bf16_f32 v9, v86, v87
	s_nop 0
	v_permlane32_swap_b32_e32 v6, v8
	s_waitcnt lgkmcnt(2)
	v_mfma_f32_32x32x16_bf16 v[112:127], v[164:167], v[148:151], v[112:127]
	v_permlane32_swap_b32_e32 v7, v9
	s_nop 0
	v_cvt_pk_bf16_f32 v2, v88, v89
	v_cvt_pk_bf16_f32 v3, v90, v91
	v_cvt_pk_bf16_f32 v4, v92, v93
	v_cvt_pk_bf16_f32 v5, v94, v95
	s_waitcnt lgkmcnt(1)
	v_mfma_f32_32x32x16_bf16 v[128:143], v[100:103], v[144:147], v[128:143]
	v_permlane32_swap_b32_e32 v2, v4
	v_permlane32_swap_b32_e32 v3, v5
	v_add_u32_e32 v234, s7, v205
	v_add_u32_e32 v235, 0xffffffa1, v234
	v_cmp_gt_i32_e32 vcc, s67, v235
	s_cmpk_gt_i32 s97, 0x7b
	s_cbranch_scc1 .Lmy_mb0_a1_1
	s_waitcnt vmcnt(3) lgkmcnt(0)
	s_barrier
.Lmy_mbj_a1_1:
	ds_read_b64_tr_b16 v[104:105], v213
	ds_read_b64_tr_b16 v[106:107], v213 offset:2048
	ds_read_b64_tr_b16 v[100:101], v213 offset:512
	ds_read_b64_tr_b16 v[102:103], v213 offset:2560
	s_waitcnt lgkmcnt(4)
	v_mfma_f32_32x32x16_bf16 v[112:127], v[214:217], v[144:147], v[112:127]
	v_add_u32_e32 v216, s7, v205
	v_mov_b32_e32 v215, v199
	s_and_saveexec_b64 s[4:5], vcc
	s_cbranch_execz .LBB0_224
	v_subrev_u32_e32 v0, 64, v216
	v_cmp_lt_i32_e32 vcc, s77, v0
	v_mov_b32_e32 v215, v198
	s_and_saveexec_b64 s[18:19], vcc
	s_cbranch_execz .LBB0_223
	ds_read2_b32 v[80:81], v211 offset1:1
	ds_read2_b32 v[82:83], v211 offset0:2 offset1:3
	ds_read2_b32 v[84:85], v211 offset0:8 offset1:9
	ds_read2_b32 v[86:87], v211 offset0:10 offset1:11
	ds_read2_b32 v[88:89], v211 offset0:16 offset1:17
	ds_read2_b32 v[90:91], v211 offset0:18 offset1:19
	ds_read2_b32 v[92:93], v211 offset0:24 offset1:25
	ds_read2_b32 v[94:95], v211 offset0:26 offset1:27
	ds_read2_b32 v[108:109], v211 offset0:32 offset1:33
	ds_read2_b32 v[110:111], v211 offset0:34 offset1:35
	ds_read2_b32 v[164:165], v211 offset0:40 offset1:41
	ds_read2_b32 v[166:167], v211 offset0:42 offset1:43
	s_waitcnt lgkmcnt(0)
	v_pk_add_f32 v[128:129], v[128:129], v[80:81]
	v_pk_add_f32 v[140:141], v[140:141], v[92:93]
	v_pk_add_f32 v[138:139], v[138:139], v[90:91]
	v_pk_add_f32 v[136:137], v[136:137], v[88:89]
	ds_read2_b32 v[80:81], v211 offset0:48 offset1:49
	ds_read2_b32 v[88:89], v211 offset0:50 offset1:51
	ds_read2_b32 v[90:91], v211 offset0:56 offset1:57
	ds_read2_b32 v[92:93], v211 offset0:58 offset1:59
	v_pk_add_f32 v[142:143], v[142:143], v[94:95]
	v_pk_add_f32 v[134:135], v[134:135], v[86:87]
	v_pk_add_f32 v[132:133], v[132:133], v[84:85]
	v_pk_add_f32 v[130:131], v[130:131], v[82:83]
	v_pk_add_f32 v[112:113], v[112:113], v[108:109]
	s_waitcnt lgkmcnt(0)
	v_pk_add_f32 v[126:127], v[126:127], v[92:93]
	v_pk_add_f32 v[124:125], v[124:125], v[90:91]
	v_pk_add_f32 v[122:123], v[122:123], v[88:89]
	v_pk_add_f32 v[120:121], v[120:121], v[80:81]
	v_pk_add_f32 v[118:119], v[118:119], v[166:167]
	v_pk_add_f32 v[116:117], v[116:117], v[164:165]
	v_pk_add_f32 v[114:115], v[114:115], v[110:111]
	v_mov_b32_e32 v215, 0

; __device__ __forceinline__ s16x4 vtr(lds_cptr p) { return __builtin_bit_cast(s16x4, __builtin_amdgcn_ds_read_tr16_b64_v4i16((__attribute__((address_space(3))) v4i16_t*)p)); }
; #define PIN(x) asm volatile("" : "+v"(x))
; template <int DK, bool NOMAX> ...
;     ...
;     if (d0 == 0) { c0 = __builtin_amdgcn_mfma_f32_32x32x16_bf16(kf[0][0], qr[0], f32x16{}, 0, 0, 0); c1 = __builtin_amdgcn_mfma_f32_32x32x16_bf16(kf[0][1], qr[0], f32x16{}, 0, 0, 0); }
;     else { c0 = __builtin_amdgcn_mfma_f32_32x32x16_bf16(kf[d0 & 1][0], qr[d0], c0, 0, 0, 0); c1 = __builtin_amdgcn_mfma_f32_32x32x16_bf16(kf[d0 & 1][1], qr[d0], c1, 0, 0, 0); }
;     if (d0 + 2 < NS) KRD_(d0 & 1, d0 + 2);
;     if constexpr (NOMAX) { }
;     else {
; #pragma unroll
;     for (int r = d0 * RPS; r < (d0 + 1) * RPS; ++r) { p1[r] = __builtin_amdgcn_exp2f(p1[r]); psa += p0[r]; }
;     if (d0 > 0) {
; #pragma unroll
;       for (int r = (d0 - 1) * RPS; r < d0 * RPS; ++r) psb += p1[r]; } }
;     if constexpr (NOMAX) {
;       if (d0 == NS / 4 - 1) { PK4R(p0, 0, pa[0]); PIN(pa[0]); }
;       if (d0 == NS / 2 - 1) { PK4R(p0, 8, pa[1]); PIN(pa[1]); }
;       if (d0 == 3 * NS / 4 - 1) { PK4R(p1, 0, pa[2]); PIN(pa[2]); }
;       if (d0 == NS - 1) { PK4R(p1, 8, pa[3]); PIN(pa[3]); }
;     } else {
;     if (d0 == NS / 2 - 1) { PK4R(p0, 0, pa[0]); PIN(pa[0]); }
;     if (d0 == NS / 2) { PK4R(p0, 8, pa[1]); PIN(pa[1]); }
;     if (d0 == NS - 1) { PK4R(p1, 0, pa[2]); PIN(pa[2]); }
;     }
;     if (d0 == NS - 1) {
;       vl[0] = vtr(vp + v_rd_off(0, 0, 0)); vh[0] = vtr(vp + v_rd_off(0, 0, 1)); vl[1] = vtr(vp + v_rd_off(1, 0, 0)); vh[1] = vtr(vp + v_rd_off(1, 0, 1)); }
;     PIN(p1); PIN(psa); PIN(psb);
.LBB0_232:
.LBB0_234:
	v_add_u32_e32 v217, s6, v187
	v_mfma_f32_32x32x16_bf16 v[96:111], v[80:83], v[156:159], 0
	v_add_u32_e32 v212, s94, v207
	ds_read_b128 v[2:5], v212
	ds_read_b128 v[218:221], v212 offset:4096
	v_cvt_pk_bf16_f32 v128, v128, v129
	v_cvt_pk_bf16_f32 v129, v130, v131
	v_cvt_pk_bf16_f32 v130, v132, v133
	v_cvt_pk_bf16_f32 v131, v134, v135
	v_mfma_f32_32x32x16_bf16 v[80:95], v[84:87], v[156:159], 0
	v_permlane32_swap_b32_e32 v128, v130
	v_permlane32_swap_b32_e32 v129, v131
	v_mfma_f32_32x32x16_bf16 v[96:111], v[6:9], v[152:155], v[96:111]
	v_add_u32_e32 v6, s94, v208
	ds_read_b128 v[132:135], v6
	ds_read_b128 v[222:225], v6 offset:4096
	v_mfma_f32_32x32x16_bf16 v[80:95], v[10:13], v[152:155], v[80:95]
	v_cvt_pk_bf16_f32 v10, v136, v137
	v_cvt_pk_bf16_f32 v11, v138, v139
	v_cvt_pk_bf16_f32 v12, v140, v141
	v_cvt_pk_bf16_f32 v13, v142, v143
	s_nop 0
	v_permlane32_swap_b32_e32 v10, v12
	v_permlane32_swap_b32_e32 v11, v13
	s_waitcnt lgkmcnt(3)
	v_mfma_f32_32x32x16_bf16 v[96:111], v[2:5], v[148:151], v[96:111]
	v_cvt_pk_bf16_f32 v6, v112, v113
	v_cvt_pk_bf16_f32 v7, v114, v115
	v_cvt_pk_bf16_f32 v8, v116, v117
	v_cvt_pk_bf16_f32 v9, v118, v119
	s_nop 0
	v_permlane32_swap_b32_e32 v6, v8
	s_waitcnt lgkmcnt(2)
	v_mfma_f32_32x32x16_bf16 v[80:95], v[218:221], v[148:151], v[80:95]
	v_permlane32_swap_b32_e32 v7, v9
	s_nop 0
	v_cvt_pk_bf16_f32 v2, v120, v121
	v_cvt_pk_bf16_f32 v3, v122, v123
	v_cvt_pk_bf16_f32 v4, v124, v125
	v_cvt_pk_bf16_f32 v5, v126, v127
	s_waitcnt lgkmcnt(1)
	v_mfma_f32_32x32x16_bf16 v[96:111], v[132:135], v[144:147], v[96:111]
	v_permlane32_swap_b32_e32 v2, v4
	v_permlane32_swap_b32_e32 v3, v5
	v_subrev_u32_e32 v234, 31, v216
	v_cmp_gt_i32_e32 vcc, s67, v234
	v_mov_b32_e32 v212, v199
	s_cmpk_gt_i32 s97, 0x7c
	s_cbranch_scc1 .Lmy_mb0_a1_2
	s_waitcnt vmcnt(3) lgkmcnt(0)
	s_barrier
.Lmy_mbj_a1_2:
	ds_read_b64_tr_b16 v[136:137], v217
	ds_read_b64_tr_b16 v[138:139], v217 offset:2048
	ds_read_b64_tr_b16 v[132:133], v217 offset:512
	ds_read_b64_tr_b16 v[134:135], v217 offset:2560
	s_waitcnt lgkmcnt(4)
	v_mfma_f32_32x32x16_bf16 v[80:95], v[222:225], v[144:147], v[80:95]
	s_and_saveexec_b64 s[4:5], vcc
	s_cbranch_execz .LBB0_238
	v_cmp_ge_i32_e32 vcc, s7, v181
	v_mov_b32_e32 v212, v198
	s_and_saveexec_b64 s[94:95], vcc
	s_cbranch_execz .LBB0_237
	ds_read2_b32 v[112:113], v211 offset0:64 offset1:65
	ds_read2_b32 v[114:115], v211 offset0:66 offset1:67
	ds_read2_b32 v[116:117], v211 offset0:72 offset1:73
	ds_read2_b32 v[118:119], v211 offset0:74 offset1:75
	ds_read2_b32 v[120:121], v211 offset0:80 offset1:81
	ds_read2_b32 v[122:123], v211 offset0:82 offset1:83
	ds_read2_b32 v[124:125], v211 offset0:88 offset1:89
	ds_read2_b32 v[126:127], v211 offset0:90 offset1:91
	ds_read2_b32 v[140:141], v211 offset0:96 offset1:97
	ds_read2_b32 v[142:143], v211 offset0:98 offset1:99
	ds_read2_b32 v[218:219], v211 offset0:104 offset1:105
	ds_read2_b32 v[220:221], v211 offset0:106 offset1:107
	s_waitcnt lgkmcnt(0)
	v_pk_add_f32 v[96:97], v[96:97], v[112:113]
	v_pk_add_f32 v[108:109], v[108:109], v[124:125]
	v_pk_add_f32 v[106:107], v[106:107], v[122:123]
	v_pk_add_f32 v[104:105], v[104:105], v[120:121]
	ds_read2_b32 v[112:113], v211 offset0:112 offset1:113
	ds_read2_b32 v[120:121], v211 offset0:114 offset1:115
	ds_read2_b32 v[122:123], v211 offset0:120 offset1:121
	ds_read2_b32 v[124:125], v211 offset0:122 offset1:123
	v_pk_add_f32 v[110:111], v[110:111], v[126:127]
	v_pk_add_f32 v[102:103], v[102:103], v[118:119]
	v_pk_add_f32 v[100:101], v[100:101], v[116:117]
	v_pk_add_f32 v[98:99], v[98:99], v[114:115]
	v_pk_add_f32 v[80:81], v[80:81], v[140:141]
	s_waitcnt lgkmcnt(0)
	v_pk_add_f32 v[94:95], v[94:95], v[124:125]
	v_pk_add_f32 v[92:93], v[92:93], v[122:123]
	v_pk_add_f32 v[90:91], v[90:91], v[120:121]
	v_pk_add_f32 v[88:89], v[88:89], v[112:113]
	v_pk_add_f32 v[86:87], v[86:87], v[220:221]
	v_pk_add_f32 v[84:85], v[84:85], v[218:219]
	v_pk_add_f32 v[82:83], v[82:83], v[142:143]
	v_mov_b32_e32 v212, 0

; __device__ __forceinline__ s16x4 vtr(lds_cptr p) { return __builtin_bit_cast(s16x4, __builtin_amdgcn_ds_read_tr16_b64_v4i16((__attribute__((address_space(3))) v4i16_t*)p)); }
; #define PIN(x) asm volatile("" : "+v"(x))
; template <int DK, bool NOMAX> ...
;     ...
;     if (d0 == 0) { c0 = __builtin_amdgcn_mfma_f32_32x32x16_bf16(kf[0][0], qr[0], f32x16{}, 0, 0, 0); c1 = __builtin_amdgcn_mfma_f32_32x32x16_bf16(kf[0][1], qr[0], f32x16{}, 0, 0, 0); }
;     else { c0 = __builtin_amdgcn_mfma_f32_32x32x16_bf16(kf[d0 & 1][0], qr[d0], c0, 0, 0, 0); c1 = __builtin_amdgcn_mfma_f32_32x32x16_bf16(kf[d0 & 1][1], qr[d0], c1, 0, 0, 0); }
;     if (d0 + 2 < NS) KRD_(d0 & 1, d0 + 2);
;     if constexpr (NOMAX) { }
;     else {
; #pragma unroll
;     for (int r = d0 * RPS; r < (d0 + 1) * RPS; ++r) { p1[r] = __builtin_amdgcn_exp2f(p1[r]); psa += p0[r]; }
;     if (d0 > 0) {
; #pragma unroll
;       for (int r = (d0 - 1) * RPS; r < d0 * RPS; ++r) psb += p1[r]; } }
;     if constexpr (NOMAX) {
;       if (d0 == NS / 4 - 1) { PK4R(p0, 0, pa[0]); PIN(pa[0]); }
;       if (d0 == NS / 2 - 1) { PK4R(p0, 8, pa[1]); PIN(pa[1]); }
;       if (d0 == 3 * NS / 4 - 1) { PK4R(p1, 0, pa[2]); PIN(pa[2]); }
;       if (d0 == NS - 1) { PK4R(p1, 8, pa[3]); PIN(pa[3]); }
;     } else {
;     if (d0 == NS / 2 - 1) { PK4R(p0, 0, pa[0]); PIN(pa[0]); }
;     if (d0 == NS / 2) { PK4R(p0, 8, pa[1]); PIN(pa[1]); }
;     if (d0 == NS - 1) { PK4R(p1, 0, pa[2]); PIN(pa[2]); }
;     }
;     if (d0 == NS - 1) {
;       vl[0] = vtr(vp + v_rd_off(0, 0, 0)); vh[0] = vtr(vp + v_rd_off(0, 0, 1)); vl[1] = vtr(vp + v_rd_off(1, 0, 0)); vh[1] = vtr(vp + v_rd_off(1, 0, 1)); }
;     PIN(p1); PIN(psa); PIN(psb);
.LBB0_313:
	s_mov_b32 s58, s95
	s_mov_b32 s95, s4
	s_add_i32 s4, s63, 0xffff4000
	s_and_b32 s59, s4, 0xc000
	s_add_i32 s4, s59, 0
	v_add_u32_e32 v213, s95, v187
	s_waitcnt lgkmcnt(0)
	v_mfma_f32_32x32x16_bf16 v[128:143], v[116:119], v[156:159], 0
	v_add_u32_e32 v0, s4, v207
	ds_read_b128 v[2:5], v0
	ds_read_b128 v[164:167], v0 offset:4096
	v_cvt_pk_bf16_f32 v96, v96, v97
	v_cvt_pk_bf16_f32 v97, v98, v99
	v_cvt_pk_bf16_f32 v98, v100, v101
	v_cvt_pk_bf16_f32 v99, v102, v103
	v_mfma_f32_32x32x16_bf16 v[112:127], v[112:115], v[156:159], 0
	v_permlane32_swap_b32_e32 v96, v98
	v_permlane32_swap_b32_e32 v97, v99
	v_mfma_f32_32x32x16_bf16 v[128:143], v[10:13], v[152:155], v[128:143]
	v_mfma_f32_32x32x16_bf16 v[112:127], v[6:9], v[152:155], v[112:127]
	v_add_u32_e32 v6, s4, v208
	ds_read_b128 v[100:103], v6
	ds_read_b128 v[214:217], v6 offset:4096
	v_cvt_pk_bf16_f32 v10, v104, v105
	v_cvt_pk_bf16_f32 v11, v106, v107
	v_cvt_pk_bf16_f32 v12, v108, v109
	v_cvt_pk_bf16_f32 v13, v110, v111
	s_nop 0
	v_permlane32_swap_b32_e32 v10, v12
	v_permlane32_swap_b32_e32 v11, v13
	s_waitcnt lgkmcnt(3)
	v_mfma_f32_32x32x16_bf16 v[128:143], v[2:5], v[148:151], v[128:143]
	v_cvt_pk_bf16_f32 v6, v80, v81
	v_cvt_pk_bf16_f32 v7, v82, v83
	v_cvt_pk_bf16_f32 v8, v84, v85
	v_cvt_pk_bf16_f32 v9, v86, v87
	s_nop 0
	v_permlane32_swap_b32_e32 v6, v8
	s_waitcnt lgkmcnt(2)
	v_mfma_f32_32x32x16_bf16 v[112:127], v[164:167], v[148:151], v[112:127]
	v_permlane32_swap_b32_e32 v7, v9
	s_nop 0
	v_cvt_pk_bf16_f32 v2, v88, v89
	v_cvt_pk_bf16_f32 v3, v90, v91
	v_cvt_pk_bf16_f32 v4, v92, v93
	v_cvt_pk_bf16_f32 v5, v94, v95
	s_waitcnt lgkmcnt(1)
	v_mfma_f32_32x32x16_bf16 v[128:143], v[100:103], v[144:147], v[128:143]
	v_permlane32_swap_b32_e32 v2, v4
	v_permlane32_swap_b32_e32 v3, v5
	v_add_u32_e32 v234, s94, v205
	v_add_u32_e32 v235, 0xffffffa1, v234
	v_cmp_gt_i32_e32 vcc, s67, v235
	s_cmp_gt_i32 s96, 59
	s_cbranch_scc1 .Lmy_mb0_a2_1
	s_waitcnt vmcnt(3) lgkmcnt(0)
	s_barrier
.Lmy_mbj_a2_1:
	ds_read_b64_tr_b16 v[104:105], v213
	ds_read_b64_tr_b16 v[106:107], v213 offset:2048
	ds_read_b64_tr_b16 v[100:101], v213 offset:512
	ds_read_b64_tr_b16 v[102:103], v213 offset:2560
	s_waitcnt lgkmcnt(4)
	v_mfma_f32_32x32x16_bf16 v[112:127], v[214:217], v[144:147], v[112:127]
	v_add_u32_e32 v216, s94, v205
	v_mov_b32_e32 v215, v199
	s_and_saveexec_b64 s[4:5], vcc
	s_cbranch_execz .LBB0_317
	v_subrev_u32_e32 v0, 64, v216
	v_cmp_lt_i32_e32 vcc, s77, v0
	v_mov_b32_e32 v215, v198
	s_and_saveexec_b64 s[16:17], vcc
	s_cbranch_execz .LBB0_316
	ds_read2_b32 v[80:81], v211 offset1:1
	ds_read2_b32 v[82:83], v211 offset0:2 offset1:3
	ds_read2_b32 v[84:85], v211 offset0:8 offset1:9
	ds_read2_b32 v[86:87], v211 offset0:10 offset1:11
	ds_read2_b32 v[88:89], v211 offset0:16 offset1:17
	ds_read2_b32 v[90:91], v211 offset0:18 offset1:19
	ds_read2_b32 v[92:93], v211 offset0:24 offset1:25
	ds_read2_b32 v[94:95], v211 offset0:26 offset1:27
	ds_read2_b32 v[108:109], v211 offset0:32 offset1:33
	ds_read2_b32 v[110:111], v211 offset0:34 offset1:35
	ds_read2_b32 v[164:165], v211 offset0:40 offset1:41
	ds_read2_b32 v[166:167], v211 offset0:42 offset1:43
	s_waitcnt lgkmcnt(0)
	v_pk_add_f32 v[128:129], v[128:129], v[80:81]
	v_pk_add_f32 v[140:141], v[140:141], v[92:93]
	v_pk_add_f32 v[138:139], v[138:139], v[90:91]
	v_pk_add_f32 v[136:137], v[136:137], v[88:89]
	ds_read2_b32 v[80:81], v211 offset0:48 offset1:49
	ds_read2_b32 v[88:89], v211 offset0:50 offset1:51
	ds_read2_b32 v[90:91], v211 offset0:56 offset1:57
	ds_read2_b32 v[92:93], v211 offset0:58 offset1:59
	v_pk_add_f32 v[142:143], v[142:143], v[94:95]
	v_pk_add_f32 v[134:135], v[134:135], v[86:87]
	v_pk_add_f32 v[132:133], v[132:133], v[84:85]
	v_pk_add_f32 v[130:131], v[130:131], v[82:83]
	v_pk_add_f32 v[112:113], v[112:113], v[108:109]
	s_waitcnt lgkmcnt(0)
	v_pk_add_f32 v[126:127], v[126:127], v[92:93]
	v_pk_add_f32 v[124:125], v[124:125], v[90:91]
	v_pk_add_f32 v[122:123], v[122:123], v[88:89]
	v_pk_add_f32 v[120:121], v[120:121], v[80:81]
	v_pk_add_f32 v[118:119], v[118:119], v[166:167]
	v_pk_add_f32 v[116:117], v[116:117], v[164:165]
	v_pk_add_f32 v[114:115], v[114:115], v[110:111]
	v_mov_b32_e32 v215, 0

; __device__ __forceinline__ s16x4 vtr(lds_cptr p) { return __builtin_bit_cast(s16x4, __builtin_amdgcn_ds_read_tr16_b64_v4i16((__attribute__((address_space(3))) v4i16_t*)p)); }
; #define PIN(x) asm volatile("" : "+v"(x))
; template <int DK, bool NOMAX> ...
;     ...
;     if (d0 == 0) { c0 = __builtin_amdgcn_mfma_f32_32x32x16_bf16(kf[0][0], qr[0], f32x16{}, 0, 0, 0); c1 = __builtin_amdgcn_mfma_f32_32x32x16_bf16(kf[0][1], qr[0], f32x16{}, 0, 0, 0); }
;     else { c0 = __builtin_amdgcn_mfma_f32_32x32x16_bf16(kf[d0 & 1][0], qr[d0], c0, 0, 0, 0); c1 = __builtin_amdgcn_mfma_f32_32x32x16_bf16(kf[d0 & 1][1], qr[d0], c1, 0, 0, 0); }
;     if (d0 + 2 < NS) KRD_(d0 & 1, d0 + 2);
;     if constexpr (NOMAX) { }
;     else {
; #pragma unroll
;     for (int r = d0 * RPS; r < (d0 + 1) * RPS; ++r) { p1[r] = __builtin_amdgcn_exp2f(p1[r]); psa += p0[r]; }
;     if (d0 > 0) {
; #pragma unroll
;       for (int r = (d0 - 1) * RPS; r < d0 * RPS; ++r) psb += p1[r]; } }
;     if constexpr (NOMAX) {
;       if (d0 == NS / 4 - 1) { PK4R(p0, 0, pa[0]); PIN(pa[0]); }
;       if (d0 == NS / 2 - 1) { PK4R(p0, 8, pa[1]); PIN(pa[1]); }
;       if (d0 == 3 * NS / 4 - 1) { PK4R(p1, 0, pa[2]); PIN(pa[2]); }
;       if (d0 == NS - 1) { PK4R(p1, 8, pa[3]); PIN(pa[3]); }
;     } else {
;     if (d0 == NS / 2 - 1) { PK4R(p0, 0, pa[0]); PIN(pa[0]); }
;     if (d0 == NS / 2) { PK4R(p0, 8, pa[1]); PIN(pa[1]); }
;     if (d0 == NS - 1) { PK4R(p1, 0, pa[2]); PIN(pa[2]); }
;     }
;     if (d0 == NS - 1) {
;       vl[0] = vtr(vp + v_rd_off(0, 0, 0)); vh[0] = vtr(vp + v_rd_off(0, 0, 1)); vl[1] = vtr(vp + v_rd_off(1, 0, 0)); vh[1] = vtr(vp + v_rd_off(1, 0, 1)); }
;     PIN(p1); PIN(psa); PIN(psb);
.LBB0_325:
.LBB0_327:
	v_add_u32_e32 v217, s58, v187
	v_mfma_f32_32x32x16_bf16 v[96:111], v[80:83], v[156:159], 0
	v_add_u32_e32 v212, s18, v207
	ds_read_b128 v[2:5], v212
	ds_read_b128 v[218:221], v212 offset:4096
	v_cvt_pk_bf16_f32 v128, v128, v129
	v_cvt_pk_bf16_f32 v129, v130, v131
	v_cvt_pk_bf16_f32 v130, v132, v133
	v_cvt_pk_bf16_f32 v131, v134, v135
	v_mfma_f32_32x32x16_bf16 v[80:95], v[84:87], v[156:159], 0
	v_permlane32_swap_b32_e32 v128, v130
	v_permlane32_swap_b32_e32 v129, v131
	v_mfma_f32_32x32x16_bf16 v[96:111], v[6:9], v[152:155], v[96:111]
	v_add_u32_e32 v6, s18, v208
	ds_read_b128 v[132:135], v6
	ds_read_b128 v[222:225], v6 offset:4096
	v_mfma_f32_32x32x16_bf16 v[80:95], v[10:13], v[152:155], v[80:95]
	v_cvt_pk_bf16_f32 v10, v136, v137
	v_cvt_pk_bf16_f32 v11, v138, v139
	v_cvt_pk_bf16_f32 v12, v140, v141
	v_cvt_pk_bf16_f32 v13, v142, v143
	s_nop 0
	v_permlane32_swap_b32_e32 v10, v12
	v_permlane32_swap_b32_e32 v11, v13
	s_waitcnt lgkmcnt(3)
	v_mfma_f32_32x32x16_bf16 v[96:111], v[2:5], v[148:151], v[96:111]
	v_cvt_pk_bf16_f32 v6, v112, v113
	v_cvt_pk_bf16_f32 v7, v114, v115
	v_cvt_pk_bf16_f32 v8, v116, v117
	v_cvt_pk_bf16_f32 v9, v118, v119
	s_nop 0
	v_permlane32_swap_b32_e32 v6, v8
	s_waitcnt lgkmcnt(2)
	v_mfma_f32_32x32x16_bf16 v[80:95], v[218:221], v[148:151], v[80:95]
	v_permlane32_swap_b32_e32 v7, v9
	s_nop 0
	v_cvt_pk_bf16_f32 v2, v120, v121
	v_cvt_pk_bf16_f32 v3, v122, v123
	v_cvt_pk_bf16_f32 v4, v124, v125
	v_cvt_pk_bf16_f32 v5, v126, v127
	s_waitcnt lgkmcnt(1)
	v_mfma_f32_32x32x16_bf16 v[96:111], v[132:135], v[144:147], v[96:111]
	v_permlane32_swap_b32_e32 v2, v4
	v_permlane32_swap_b32_e32 v3, v5
	v_subrev_u32_e32 v234, 31, v216
	v_cmp_gt_i32_e32 vcc, s67, v234
	v_mov_b32_e32 v212, v199
	s_cmp_gt_i32 s96, 60
	s_cbranch_scc1 .Lmy_mb0_a2_2
	s_waitcnt vmcnt(3) lgkmcnt(0)
	s_barrier
.Lmy_mbj_a2_2:
	ds_read_b64_tr_b16 v[136:137], v217
	ds_read_b64_tr_b16 v[138:139], v217 offset:2048
	ds_read_b64_tr_b16 v[132:133], v217 offset:512
	ds_read_b64_tr_b16 v[134:135], v217 offset:2560
	s_waitcnt lgkmcnt(4)
	v_mfma_f32_32x32x16_bf16 v[80:95], v[222:225], v[144:147], v[80:95]
	s_and_saveexec_b64 s[4:5], vcc
	s_cbranch_execz .LBB0_331
	v_cmp_ge_i32_e32 vcc, s94, v181
	v_mov_b32_e32 v212, v198
	s_and_saveexec_b64 s[18:19], vcc
	s_cbranch_execz .LBB0_330
	ds_read2_b32 v[112:113], v211 offset0:64 offset1:65
	ds_read2_b32 v[114:115], v211 offset0:66 offset1:67
	ds_read2_b32 v[116:117], v211 offset0:72 offset1:73
	ds_read2_b32 v[118:119], v211 offset0:74 offset1:75
	ds_read2_b32 v[120:121], v211 offset0:80 offset1:81
	ds_read2_b32 v[122:123], v211 offset0:82 offset1:83
	ds_read2_b32 v[124:125], v211 offset0:88 offset1:89
	ds_read2_b32 v[126:127], v211 offset0:90 offset1:91
	ds_read2_b32 v[140:141], v211 offset0:96 offset1:97
	ds_read2_b32 v[142:143], v211 offset0:98 offset1:99
	ds_read2_b32 v[218:219], v211 offset0:104 offset1:105
	ds_read2_b32 v[220:221], v211 offset0:106 offset1:107
	s_waitcnt lgkmcnt(0)
	v_pk_add_f32 v[96:97], v[96:97], v[112:113]
	v_pk_add_f32 v[108:109], v[108:109], v[124:125]
	v_pk_add_f32 v[106:107], v[106:107], v[122:123]
	v_pk_add_f32 v[104:105], v[104:105], v[120:121]
	ds_read2_b32 v[112:113], v211 offset0:112 offset1:113
	ds_read2_b32 v[120:121], v211 offset0:114 offset1:115
	ds_read2_b32 v[122:123], v211 offset0:120 offset1:121
	ds_read2_b32 v[124:125], v211 offset0:122 offset1:123
	v_pk_add_f32 v[110:111], v[110:111], v[126:127]
	v_pk_add_f32 v[102:103], v[102:103], v[118:119]
	v_pk_add_f32 v[100:101], v[100:101], v[116:117]
	v_pk_add_f32 v[98:99], v[98:99], v[114:115]
	v_pk_add_f32 v[80:81], v[80:81], v[140:141]
	s_waitcnt lgkmcnt(0)
	v_pk_add_f32 v[94:95], v[94:95], v[124:125]
	v_pk_add_f32 v[92:93], v[92:93], v[122:123]
	v_pk_add_f32 v[90:91], v[90:91], v[120:121]
	v_pk_add_f32 v[88:89], v[88:89], v[112:113]
	v_pk_add_f32 v[86:87], v[86:87], v[220:221]
	v_pk_add_f32 v[84:85], v[84:85], v[218:219]
	v_pk_add_f32 v[82:83], v[82:83], v[142:143]
	v_mov_b32_e32 v212, 0
